# v19 with transpose tile split 13 per low CU (balances hyena-filter CUs against mod+transpose CUs)
# baseline (speedup 1.0000x reference)
.LBB0_87:
	s_load_dwordx16 s[4:19], s[0:1], 0xc0
	s_cmpk_gt_i32 s54, 0x17ff
	s_waitcnt lgkmcnt(0)
	v_writelane_b32 v253, s4, 12
	s_nop 1
	v_writelane_b32 v253, s5, 13
	v_writelane_b32 v253, s6, 14
	v_writelane_b32 v253, s7, 15
	v_writelane_b32 v253, s8, 16
	v_writelane_b32 v253, s9, 17
	v_writelane_b32 v253, s10, 18
	v_writelane_b32 v253, s11, 19
	v_writelane_b32 v253, s12, 20
	v_writelane_b32 v253, s13, 21
	v_writelane_b32 v253, s14, 22
	v_writelane_b32 v253, s15, 23
	v_writelane_b32 v253, s16, 24
	v_writelane_b32 v253, s17, 25
	v_writelane_b32 v253, s18, 26
	v_writelane_b32 v253, s19, 27
	s_cbranch_scc1 .LBB0_143
	s_load_dwordx2 s[4:5], s[0:1], 0x40
	s_load_dwordx2 s[6:7], s[0:1], 0xe8
	s_load_dwordx4 s[8:11], s[0:1], 0xf0
	s_load_dwordx2 s[12:13], s[0:1], 0x110
	s_movk_i32 s15, 0x70
	s_add_i32 s14, s54, 1728
	s_movk_i32 s16, 0x17ff
	s_cmp_lt_u32 s54, 0x90
	s_cbranch_scc0 .Ltr_hi
	s_movk_i32 s15, 0x90
	s_mov_b32 s14, s54
	s_movk_i32 s16, 1871
